# S5 prompt item output stage: waves 4-7 start ~0.6us later (s_sleep 24) so the partner waves' MFMA loops and gelu epilogues interleave (stagger)
# speedup vs baseline: 1.0107x; 1.0039x over previous
; #define LAS __attribute__((address_space(3)))
; #define S5_LAUNDER() int tid_ = tid0, lane_ = lane0; asm volatile("" : "+v"(tid_), "+v"(lane_)); const int tid = tid_, lane = lane_, fr = lane & 15, fq = lane >> 4; (void)tid; (void)fr; (void)fq
; #define S5_LOADK(FA_, UB_, KS_) do { FA_ = *(const LAS bf16x8*)(lds + R2_OFF + ((tau - 2 * (KS_)) * 64 + lane) * 16); \
;         _Pragma("unroll") for (int cb = 0; cb < 4; ++cb) UB_[cb] = *(const LAS bf16x8*)(lds + U_OFF + (16 * cb + fr) * 1056 + (2 * (KS_) + (fq >> 1)) * 32 + 16 * (fq & 1)); } while (0)
; __device__ __forceinline__ void s5_prompt_item_mfma(LAS unsigned char* lds, int tid0, int lane0, int wave, int n, int g, const bf16* USg, const bf16* FTg, const bf16* WTg, const bf16* GTg, ...
;     ...
;     S5_LAUNDER();
; #pragma unroll
;     for (int it = 0; it < 4; ++it) { const int q = tid + 512 * it; *(LAS v4u*)(lds + R2_OFF + q * 16) = ftq[it]; }
;     const f32x4 dk = *(const f32x4*)(dsk + 4 * fq);
;     __syncthreads();
;     bf16x8 hbv[4][4];
; #pragma unroll
;     for (int kk = 0; kk < 4; ++kk)
; #pragma unroll
;         for (int cb = 0; cb < 4; ++cb) hbv[kk][cb] = *(const LAS bf16x8*)(lds + HP_OFF + (16 * cb + fr) * 272 + 64 * kk + 16 * fq);
;     ...
; #pragma unroll
;     for (int j = 0; j < 4; ++j) {
;         const int tau = (j == 0) ? tau0 : (j == 1) ? tau1 : (j == 2) ? tau2 : tau3;
;         f32x4 acc[4];
; #pragma unroll
;         for (int cb = 0; cb < 4; ++cb) acc[cb] = (f32x4){0.f, 0.f, 0.f, 0.f};
;         {
;             const int nks = (tau >> 1) + 1;
;             bf16x8 fa0, fa1, ub0[4], ub1[4];
;             S5_LOADK(fa0, ub0, 0);
.LBB0_852:
	s_or_b64 exec, exec, s[54:55]
	v_mov_b32_e32 v201, v196
	v_mov_b32_e32 v2, v192
	s_lshl_b32 s10, s65, 6
	s_barrier
	s_add_u32 s10, s52, s10
	v_ashrrev_i32_e32 v202, 4, v201
	v_lshlrev_b32_e32 v194, 2, v202
	s_addc_u32 s11, s53, 0
	v_ashrrev_i32_e32 v195, 31, v194
	v_lshl_add_u64 v[20:21], v[194:195], 2, s[10:11]
	global_load_dwordx4 v[20:23], v[20:21], off
	s_add_i32 s10, 0, 0x10800
	v_and_b32_e32 v203, 15, v201
	v_lshl_add_u32 v2, v2, 4, s10
	s_waitcnt vmcnt(20)
	ds_write_b128 v2, v[24:27]
	s_waitcnt vmcnt(19)
	ds_write_b128 v2, v[28:31] offset:8192
	s_waitcnt vmcnt(18)
	ds_write_b128 v2, v[32:35] offset:16384
	s_waitcnt vmcnt(17)
	ds_write_b128 v2, v[36:39] offset:24576
	v_and_b32_e32 v2, -16, v201
	s_add_i32 s11, 0, 0x18c00
	v_mul_u32_u24_e32 v24, 0x110, v203
	v_add3_u32 v2, s11, v2, v24
	s_waitcnt lgkmcnt(0)
	s_barrier
	v_readfirstlane_b32 s99, v192
	s_nop 3
	s_lshr_b32 s99, s99, 6
	s_cmp_lt_u32 s99, 4
	s_cbranch_scc1 .Ls5_stag
	s_sleep 24
.Ls5_stag:
	ds_read_b128 v[84:87], v2
	ds_read_b128 v[76:79], v2 offset:64
	ds_read_b128 v[68:71], v2 offset:4352
	ds_read_b128 v[56:59], v2 offset:4416
	ds_read_b128 v[64:67], v2 offset:8704
	ds_read_b128 v[48:51], v2 offset:8768
	ds_read_b128 v[60:63], v2 offset:13056
	ds_read_b128 v[44:47], v2 offset:13120
	ds_read_b128 v[80:83], v2 offset:128
	ds_read_b128 v[72:75], v2 offset:192
	ds_read_b128 v[52:55], v2 offset:4480
	ds_read_b128 v[32:35], v2 offset:4544
	ds_read_b128 v[40:43], v2 offset:8832
	ds_read_b128 v[28:31], v2 offset:8896
	ds_read_b128 v[36:39], v2 offset:13184
	ds_read_b128 v[24:27], v2 offset:13248
	v_and_b32_e32 v2, 16, v201
	v_add_u32_e32 v193, 0, v2
	v_and_b32_e32 v2, 0xffffffe0, v201
	v_lshlrev_b32_e32 v198, 4, v201
	v_add_u32_e32 v88, v193, v2
	v_mul_u32_u24_e32 v2, 0x420, v203
	v_mov_b32_e32 v163, 0
	v_add_u32_e32 v199, s10, v198
	s_andn2_b64 vcc, exec, s[78:79]
	v_add_u32_e32 v200, v88, v2
	v_add_u32_e32 v197, 64, v201
	v_mov_b32_e32 v162, v163
	v_mov_b32_e32 v161, v163
	v_mov_b32_e32 v160, v163
	v_mov_b32_e32 v167, v163
	v_mov_b32_e32 v166, v163
	v_mov_b32_e32 v165, v163
	v_mov_b32_e32 v164, v163
	v_mov_b32_e32 v171, v163
	v_mov_b32_e32 v170, v163
	v_mov_b32_e32 v169, v163
	v_mov_b32_e32 v168, v163
	v_mov_b32_e32 v159, v163
	v_mov_b32_e32 v158, v163
	v_mov_b32_e32 v157, v163
	v_mov_b32_e32 v156, v163
	s_mov_b32 s74, s37
	s_mov_b32 s75, s84
	s_cbranch_vccnz .LBB0_861
	ds_read_b128 v[172:175], v200 offset:16896
	ds_read_b128 v[176:179], v200
	ds_read_b128 v[184:187], v200 offset:50688
	v_readlane_b32 s10, v253, 57
	v_mov_b32_e32 v156, 0
	v_add_u32_e32 v204, 64, v201
	v_add_u32_e32 v88, s10, v199
	ds_read_b128 v[188:191], v200 offset:33792
	ds_read_b128 v[180:183], v88
	v_readlane_b32 s10, v254, 44
	s_mov_b32 s14, 2
	v_mov_b32_e32 v157, v156
	v_add_u32_e32 v205, s10, v198
	v_mov_b32_e32 v158, v156
	v_mov_b32_e32 v159, v156
	v_mov_b32_e32 v168, v156
	v_mov_b32_e32 v169, v156
	v_mov_b32_e32 v170, v156
	v_mov_b32_e32 v171, v156
	v_mov_b32_e32 v164, v156
	v_mov_b32_e32 v165, v156
	v_mov_b32_e32 v166, v156
	v_mov_b32_e32 v167, v156
	v_mov_b32_e32 v160, v156
	v_mov_b32_e32 v161, v156
	v_mov_b32_e32 v162, v156
	v_mov_b32_e32 v163, v156
	s_branch .LBB0_855
